# Wout-GEMM residual epilogue with full-line accesses (bpermute-transposed accumulators, 8 rows x 128 B per access), on top of the same change in the Down GEMM
# speedup vs baseline: 1.0555x; 1.0126x over previous
;   DI void operator()(const pg8::f32x4 (&acc)[2][2][4][2], const pg8::Unit& u, int wr, int wc, int fr, int fq) const {
;     const int row0 = u.pm * 256 + wr * 64 + fr, col0 = u.pn * 256 + wc * 32 + 8 * fq;
;     const int b = (u.pm * 256) / TT;
; #pragma unroll
;     for (int ai = 0; ai < 2; ++ai)
; #pragma unroll
;       for (int m = 0; m < 4; ++m) {
;         const int row = row0 + ai * 128 + m * 16;
;         const int t = row - b * TT;
;         const bool isc = t >= TL;
;         float* dst = isc ? xc + ((size_t)b * TC + (t - TL)) * DM : xout + ((size_t)b * TL + t) * DM;
;         const float* src = src_input ? (isc ? cin + ((size_t)b * TC + (t - TL)) * DM : xin + ((size_t)b * TL + t) * DM) : dst;
;         const float* gate = modl + (size_t)(isc ? 16 : b) * 6144 + gi * DM;
; #pragma unroll
;         for (int bj = 0; bj < 2; ++bj) {
;           const int col = col0 + bj * 128;
; #pragma unroll
;           for (int n = 0; n < 2; ++n) {
;             pg8::f32x4 sv = *(const pg8::f32x4*)(src + col + 4 * n);
;             pg8::f32x4 gv = *(const pg8::f32x4*)(gate + col + 4 * n);
;             pg8::f32x4 o = sv + gv * acc[ai][bj][m][n];
;             *(pg8::f32x4*)(dst + col + 4 * n) = o;
;           }
;         }
;       }
;   }
.LBB0_1141:
	v_lshl_or_b32 v142, s30, 8, v150
	v_mov_b32_e32 v141, s34
	v_ashrrev_i32_e32 v143, 31, v142
	v_cndmask_b32_e64 v141, v141, 16, s[8:9]
	v_mov_b64_e32 v[154:155], s[20:21]
	s_movk_i32 s8, 0x6000
	v_lshlrev_b64 v[142:143], 2, v[142:143]
	v_mad_i64_i32 v[154:155], s[8:9], v141, s8, v[154:155]
	v_lshl_add_u64 v[162:163], v[146:147], 0, v[142:143]
	v_lshl_add_u64 v[164:165], v[154:155], 0, v[142:143]
	v_lshl_add_u64 v[166:167], v[144:145], 0, v[142:143]
	s_mov_b32 s10, 0xaaaaaaaa
	s_mov_b32 s11, 0xaaaaaaaa
	s_mov_b64 s[50:51], 0x10000
	s_mov_b64 s[8:9], 0x50000
	v_and_b32_e32 v158, 63, v182
	v_lshrrev_b32_e32 v159, 3, v158
	v_and_b32_e32 v160, 7, v158
	v_lshrrev_b32_e32 v210, 1, v160
	v_lshl_add_u32 v210, v210, 4, v159
	v_lshlrev_b32_e32 v210, 2, v210
	v_add_u32_e32 v211, 32, v210
	v_lshrrev_b32_e32 v161, 4, v158
	v_and_b32_e32 v168, 15, v158
	v_lshlrev_b32_e32 v169, 4, v160
	v_lshlrev_b32_e32 v161, 5, v161
	v_sub_u32_e32 v169, v169, v161
	v_sub_u32_e32 v170, v159, v168
	v_lshl_add_u32 v170, v170, 12, v169
	v_ashrrev_i32_e32 v171, 31, v170
	v_ashrrev_i32_e32 v168, 31, v169
	v_add_co_u32_e32 v212, vcc, v162, v170
	s_nop 1
	v_addc_co_u32_e32 v213, vcc, v163, v171, vcc
	v_add_co_u32_e32 v216, vcc, v166, v170
	s_nop 1
	v_addc_co_u32_e32 v217, vcc, v167, v171, vcc
	v_lshl_add_u64 v[214:215], v[212:213], 0, s[50:51]
	v_add_co_u32_e32 v214, vcc, 0xffff8000, v214
	s_nop 1
	v_addc_co_u32_e32 v215, vcc, -1, v215, vcc
	v_lshl_add_u64 v[218:219], v[216:217], 0, s[50:51]
	v_add_co_u32_e32 v218, vcc, 0xffff8000, v218
	s_nop 1
	v_addc_co_u32_e32 v219, vcc, -1, v219, vcc
	v_add_co_u32_e32 v164, vcc, v164, v169
	s_nop 1
	v_addc_co_u32_e32 v165, vcc, v165, v168, vcc
	global_load_dwordx4 v[202:205], v[164:165], off
	global_load_dwordx4 v[206:209], v[164:165], off offset:512
	global_load_dwordx4 v[220:223], v[212:213], off
	global_load_dwordx4 v[224:227], v[214:215], off
	global_load_dwordx4 v[228:231], v[212:213], off offset:512
	global_load_dwordx4 v[232:235], v[214:215], off offset:512
	v_lshl_add_u64 v[212:213], v[212:213], 0, s[50:51]
	v_lshl_add_u64 v[214:215], v[214:215], 0, s[50:51]
	global_load_dwordx4 v[236:239], v[212:213], off
	global_load_dwordx4 v[240:243], v[214:215], off
	global_load_dwordx4 v[244:247], v[212:213], off offset:512
	global_load_dwordx4 v[248:251], v[214:215], off offset:512
	s_waitcnt vmcnt(4)
	ds_bpermute_b32 v140, v210, v124
	ds_bpermute_b32 v144, v210, v120
	ds_bpermute_b32 v141, v210, v125
	ds_bpermute_b32 v145, v210, v121
	ds_bpermute_b32 v142, v210, v126
	ds_bpermute_b32 v146, v210, v122
	ds_bpermute_b32 v143, v210, v127
	ds_bpermute_b32 v147, v210, v123
	s_waitcnt lgkmcnt(0)
	v_cndmask_b32_e64 v154, v140, v144, s[10:11]
	v_cndmask_b32_e64 v155, v141, v145, s[10:11]
	v_cndmask_b32_e64 v156, v142, v146, s[10:11]
	v_cndmask_b32_e64 v157, v143, v147, s[10:11]
	v_pk_fma_f32 v[222:223], v[156:157], v[204:205], v[222:223]
	v_pk_fma_f32 v[220:221], v[154:155], v[202:203], v[220:221]
	global_store_dwordx4 v[216:217], v[220:223], off
	ds_bpermute_b32 v140, v211, v124
	ds_bpermute_b32 v144, v211, v120
	ds_bpermute_b32 v141, v211, v125
	ds_bpermute_b32 v145, v211, v121
	ds_bpermute_b32 v142, v211, v126
	ds_bpermute_b32 v146, v211, v122
	ds_bpermute_b32 v143, v211, v127
	ds_bpermute_b32 v147, v211, v123
	s_waitcnt lgkmcnt(0)
	v_cndmask_b32_e64 v154, v140, v144, s[10:11]
	v_cndmask_b32_e64 v155, v141, v145, s[10:11]
	v_cndmask_b32_e64 v156, v142, v146, s[10:11]
	v_cndmask_b32_e64 v157, v143, v147, s[10:11]
	v_pk_fma_f32 v[226:227], v[156:157], v[204:205], v[226:227]
	v_pk_fma_f32 v[224:225], v[154:155], v[202:203], v[224:225]
	global_store_dwordx4 v[218:219], v[224:227], off
	ds_bpermute_b32 v140, v210, v116
	ds_bpermute_b32 v144, v210, v112
	ds_bpermute_b32 v141, v210, v117
	ds_bpermute_b32 v145, v210, v113
	ds_bpermute_b32 v142, v210, v118
	ds_bpermute_b32 v146, v210, v114
	ds_bpermute_b32 v143, v210, v119
	ds_bpermute_b32 v147, v210, v115
	s_waitcnt lgkmcnt(0)
	v_cndmask_b32_e64 v154, v140, v144, s[10:11]
	v_cndmask_b32_e64 v155, v141, v145, s[10:11]
	v_cndmask_b32_e64 v156, v142, v146, s[10:11]
	v_cndmask_b32_e64 v157, v143, v147, s[10:11]
	v_pk_fma_f32 v[230:231], v[156:157], v[208:209], v[230:231]
	v_pk_fma_f32 v[228:229], v[154:155], v[206:207], v[228:229]
	global_store_dwordx4 v[216:217], v[228:231], off offset:512
	ds_bpermute_b32 v140, v211, v116
	ds_bpermute_b32 v144, v211, v112
	ds_bpermute_b32 v141, v211, v117
	ds_bpermute_b32 v145, v211, v113
	ds_bpermute_b32 v142, v211, v118
	ds_bpermute_b32 v146, v211, v114
	ds_bpermute_b32 v143, v211, v119
	ds_bpermute_b32 v147, v211, v115
	s_waitcnt lgkmcnt(0)
	v_cndmask_b32_e64 v154, v140, v144, s[10:11]
	v_cndmask_b32_e64 v155, v141, v145, s[10:11]
	v_cndmask_b32_e64 v156, v142, v146, s[10:11]
	v_cndmask_b32_e64 v157, v143, v147, s[10:11]
	v_pk_fma_f32 v[234:235], v[156:157], v[208:209], v[234:235]
	v_pk_fma_f32 v[232:233], v[154:155], v[206:207], v[232:233]
	global_store_dwordx4 v[218:219], v[232:235], off offset:512
	v_lshl_add_u64 v[212:213], v[212:213], 0, s[50:51]
	v_lshl_add_u64 v[214:215], v[214:215], 0, s[50:51]
	global_load_dwordx4 v[220:223], v[212:213], off
	global_load_dwordx4 v[224:227], v[214:215], off
	global_load_dwordx4 v[228:231], v[212:213], off offset:512
	global_load_dwordx4 v[232:235], v[214:215], off offset:512
	s_waitcnt vmcnt(8)
	v_lshl_add_u64 v[216:217], v[216:217], 0, s[50:51]
	v_lshl_add_u64 v[218:219], v[218:219], 0, s[50:51]
	ds_bpermute_b32 v140, v210, v108
	ds_bpermute_b32 v144, v210, v104
	ds_bpermute_b32 v141, v210, v109
	ds_bpermute_b32 v145, v210, v105
	ds_bpermute_b32 v142, v210, v110
	ds_bpermute_b32 v146, v210, v106
	ds_bpermute_b32 v143, v210, v111
	ds_bpermute_b32 v147, v210, v107
	s_waitcnt lgkmcnt(0)
;   DI void operator()(const pg8::f32x4 (&acc)[2][2][4][2], const pg8::Unit& u, int wr, int wc, int fr, int fq) const {
;     const int row0 = u.pm * 256 + wr * 64 + fr, col0 = u.pn * 256 + wc * 32 + 8 * fq;
;     const int b = (u.pm * 256) / TT;
; #pragma unroll
;     for (int ai = 0; ai < 2; ++ai)
; #pragma unroll
;       for (int m = 0; m < 4; ++m) {
;         const int row = row0 + ai * 128 + m * 16;
;         const int t = row - b * TT;
;         const bool isc = t >= TL;
;         float* dst = isc ? xc + ((size_t)b * TC + (t - TL)) * DM : xout + ((size_t)b * TL + t) * DM;
;         const float* src = src_input ? (isc ? cin + ((size_t)b * TC + (t - TL)) * DM : xin + ((size_t)b * TL + t) * DM) : dst;
;         const float* gate = modl + (size_t)(isc ? 16 : b) * 6144 + gi * DM;
; #pragma unroll
;         for (int bj = 0; bj < 2; ++bj) {
;           const int col = col0 + bj * 128;
; #pragma unroll
;           for (int n = 0; n < 2; ++n) {
;             pg8::f32x4 sv = *(const pg8::f32x4*)(src + col + 4 * n);
;             pg8::f32x4 gv = *(const pg8::f32x4*)(gate + col + 4 * n);
;             pg8::f32x4 o = sv + gv * acc[ai][bj][m][n];
;             *(pg8::f32x4*)(dst + col + 4 * n) = o;
;           }
;         }
;       }
;   }
	v_cndmask_b32_e64 v154, v140, v144, s[10:11]
	v_cndmask_b32_e64 v155, v141, v145, s[10:11]
	v_cndmask_b32_e64 v156, v142, v146, s[10:11]
	v_cndmask_b32_e64 v157, v143, v147, s[10:11]
	v_pk_fma_f32 v[238:239], v[156:157], v[204:205], v[238:239]
	v_pk_fma_f32 v[236:237], v[154:155], v[202:203], v[236:237]
	global_store_dwordx4 v[216:217], v[236:239], off
	ds_bpermute_b32 v140, v211, v108
	ds_bpermute_b32 v144, v211, v104
	ds_bpermute_b32 v141, v211, v109
	ds_bpermute_b32 v145, v211, v105
	ds_bpermute_b32 v142, v211, v110
	ds_bpermute_b32 v146, v211, v106
	ds_bpermute_b32 v143, v211, v111
	ds_bpermute_b32 v147, v211, v107
	s_waitcnt lgkmcnt(0)
	v_cndmask_b32_e64 v154, v140, v144, s[10:11]
	v_cndmask_b32_e64 v155, v141, v145, s[10:11]
	v_cndmask_b32_e64 v156, v142, v146, s[10:11]
	v_cndmask_b32_e64 v157, v143, v147, s[10:11]
	v_pk_fma_f32 v[242:243], v[156:157], v[204:205], v[242:243]
	v_pk_fma_f32 v[240:241], v[154:155], v[202:203], v[240:241]
	global_store_dwordx4 v[218:219], v[240:243], off
	ds_bpermute_b32 v140, v210, v100
	ds_bpermute_b32 v144, v210, v96
	ds_bpermute_b32 v141, v210, v101
	ds_bpermute_b32 v145, v210, v97
	ds_bpermute_b32 v142, v210, v102
	ds_bpermute_b32 v146, v210, v98
	ds_bpermute_b32 v143, v210, v103
	ds_bpermute_b32 v147, v210, v99
	s_waitcnt lgkmcnt(0)
	v_cndmask_b32_e64 v154, v140, v144, s[10:11]
	v_cndmask_b32_e64 v155, v141, v145, s[10:11]
	v_cndmask_b32_e64 v156, v142, v146, s[10:11]
	v_cndmask_b32_e64 v157, v143, v147, s[10:11]
	v_pk_fma_f32 v[246:247], v[156:157], v[208:209], v[246:247]
	v_pk_fma_f32 v[244:245], v[154:155], v[206:207], v[244:245]
	global_store_dwordx4 v[216:217], v[244:247], off offset:512
	ds_bpermute_b32 v140, v211, v100
	ds_bpermute_b32 v144, v211, v96
	ds_bpermute_b32 v141, v211, v101
	ds_bpermute_b32 v145, v211, v97
	ds_bpermute_b32 v142, v211, v102
	ds_bpermute_b32 v146, v211, v98
	ds_bpermute_b32 v143, v211, v103
	ds_bpermute_b32 v147, v211, v99
	s_waitcnt lgkmcnt(0)
	v_cndmask_b32_e64 v154, v140, v144, s[10:11]
	v_cndmask_b32_e64 v155, v141, v145, s[10:11]
	v_cndmask_b32_e64 v156, v142, v146, s[10:11]
	v_cndmask_b32_e64 v157, v143, v147, s[10:11]
	v_pk_fma_f32 v[250:251], v[156:157], v[208:209], v[250:251]
	v_pk_fma_f32 v[248:249], v[154:155], v[206:207], v[248:249]
	global_store_dwordx4 v[218:219], v[248:251], off offset:512
	v_lshl_add_u64 v[212:213], v[212:213], 0, s[50:51]
	v_lshl_add_u64 v[214:215], v[214:215], 0, s[50:51]
	global_load_dwordx4 v[236:239], v[212:213], off
	global_load_dwordx4 v[240:243], v[214:215], off
	global_load_dwordx4 v[244:247], v[212:213], off offset:512
	global_load_dwordx4 v[248:251], v[214:215], off offset:512
	s_waitcnt vmcnt(8)
	v_lshl_add_u64 v[216:217], v[216:217], 0, s[50:51]
	v_lshl_add_u64 v[218:219], v[218:219], 0, s[50:51]
	ds_bpermute_b32 v140, v210, v92
	ds_bpermute_b32 v144, v210, v88
	ds_bpermute_b32 v141, v210, v93
	ds_bpermute_b32 v145, v210, v89
	ds_bpermute_b32 v142, v210, v94
	ds_bpermute_b32 v146, v210, v90
	ds_bpermute_b32 v143, v210, v95
	ds_bpermute_b32 v147, v210, v91
	s_waitcnt lgkmcnt(0)
	v_cndmask_b32_e64 v154, v140, v144, s[10:11]
	v_cndmask_b32_e64 v155, v141, v145, s[10:11]
	v_cndmask_b32_e64 v156, v142, v146, s[10:11]
	v_cndmask_b32_e64 v157, v143, v147, s[10:11]
	v_pk_fma_f32 v[222:223], v[156:157], v[204:205], v[222:223]
	v_pk_fma_f32 v[220:221], v[154:155], v[202:203], v[220:221]
	global_store_dwordx4 v[216:217], v[220:223], off
	ds_bpermute_b32 v140, v211, v92
	ds_bpermute_b32 v144, v211, v88
	ds_bpermute_b32 v141, v211, v93
	ds_bpermute_b32 v145, v211, v89
	ds_bpermute_b32 v142, v211, v94
	ds_bpermute_b32 v146, v211, v90
	ds_bpermute_b32 v143, v211, v95
	ds_bpermute_b32 v147, v211, v91
	s_waitcnt lgkmcnt(0)
	v_cndmask_b32_e64 v154, v140, v144, s[10:11]
	v_cndmask_b32_e64 v155, v141, v145, s[10:11]
	v_cndmask_b32_e64 v156, v142, v146, s[10:11]
	v_cndmask_b32_e64 v157, v143, v147, s[10:11]
	v_pk_fma_f32 v[226:227], v[156:157], v[204:205], v[226:227]
	v_pk_fma_f32 v[224:225], v[154:155], v[202:203], v[224:225]
	global_store_dwordx4 v[218:219], v[224:227], off
	ds_bpermute_b32 v140, v210, v84
	ds_bpermute_b32 v144, v210, v80
	ds_bpermute_b32 v141, v210, v85
	ds_bpermute_b32 v145, v210, v81
	ds_bpermute_b32 v142, v210, v86
	ds_bpermute_b32 v146, v210, v82
	ds_bpermute_b32 v143, v210, v87
	ds_bpermute_b32 v147, v210, v83
	s_waitcnt lgkmcnt(0)
	v_cndmask_b32_e64 v154, v140, v144, s[10:11]
	v_cndmask_b32_e64 v155, v141, v145, s[10:11]
	v_cndmask_b32_e64 v156, v142, v146, s[10:11]
	v_cndmask_b32_e64 v157, v143, v147, s[10:11]
	v_pk_fma_f32 v[230:231], v[156:157], v[208:209], v[230:231]
	v_pk_fma_f32 v[228:229], v[154:155], v[206:207], v[228:229]
	global_store_dwordx4 v[216:217], v[228:231], off offset:512
	ds_bpermute_b32 v140, v211, v84
	ds_bpermute_b32 v144, v211, v80
	ds_bpermute_b32 v141, v211, v85
	ds_bpermute_b32 v145, v211, v81
	ds_bpermute_b32 v142, v211, v86
	ds_bpermute_b32 v146, v211, v82
	ds_bpermute_b32 v143, v211, v87
	ds_bpermute_b32 v147, v211, v83
	s_waitcnt lgkmcnt(0)
	v_cndmask_b32_e64 v154, v140, v144, s[10:11]
	v_cndmask_b32_e64 v155, v141, v145, s[10:11]
	v_cndmask_b32_e64 v156, v142, v146, s[10:11]
	v_cndmask_b32_e64 v157, v143, v147, s[10:11]
	v_pk_fma_f32 v[234:235], v[156:157], v[208:209], v[234:235]
	v_pk_fma_f32 v[232:233], v[154:155], v[206:207], v[232:233]
	global_store_dwordx4 v[218:219], v[232:235], off offset:512
	v_lshl_add_u64 v[212:213], v[212:213], 0, s[8:9]
	v_lshl_add_u64 v[214:215], v[214:215], 0, s[8:9]
	global_load_dwordx4 v[220:223], v[212:213], off
	global_load_dwordx4 v[224:227], v[214:215], off
	global_load_dwordx4 v[228:231], v[212:213], off offset:512
	global_load_dwordx4 v[232:235], v[214:215], off offset:512
	s_waitcnt vmcnt(8)
;   DI void operator()(const pg8::f32x4 (&acc)[2][2][4][2], const pg8::Unit& u, int wr, int wc, int fr, int fq) const {
;     const int row0 = u.pm * 256 + wr * 64 + fr, col0 = u.pn * 256 + wc * 32 + 8 * fq;
;     const int b = (u.pm * 256) / TT;
; #pragma unroll
;     for (int ai = 0; ai < 2; ++ai)
; #pragma unroll
;       for (int m = 0; m < 4; ++m) {
;         const int row = row0 + ai * 128 + m * 16;
;         const int t = row - b * TT;
;         const bool isc = t >= TL;
;         float* dst = isc ? xc + ((size_t)b * TC + (t - TL)) * DM : xout + ((size_t)b * TL + t) * DM;
;         const float* src = src_input ? (isc ? cin + ((size_t)b * TC + (t - TL)) * DM : xin + ((size_t)b * TL + t) * DM) : dst;
;         const float* gate = modl + (size_t)(isc ? 16 : b) * 6144 + gi * DM;
; #pragma unroll
;         for (int bj = 0; bj < 2; ++bj) {
;           const int col = col0 + bj * 128;
; #pragma unroll
;           for (int n = 0; n < 2; ++n) {
;             pg8::f32x4 sv = *(const pg8::f32x4*)(src + col + 4 * n);
;             pg8::f32x4 gv = *(const pg8::f32x4*)(gate + col + 4 * n);
;             pg8::f32x4 o = sv + gv * acc[ai][bj][m][n];
;             *(pg8::f32x4*)(dst + col + 4 * n) = o;
;           }
;         }
;       }
;   }
	v_lshl_add_u64 v[216:217], v[216:217], 0, s[50:51]
	v_lshl_add_u64 v[218:219], v[218:219], 0, s[50:51]
	ds_bpermute_b32 v140, v210, v76
	ds_bpermute_b32 v144, v210, v72
	ds_bpermute_b32 v141, v210, v77
	ds_bpermute_b32 v145, v210, v73
	ds_bpermute_b32 v142, v210, v78
	ds_bpermute_b32 v146, v210, v74
	ds_bpermute_b32 v143, v210, v79
	ds_bpermute_b32 v147, v210, v75
	s_waitcnt lgkmcnt(0)
	v_cndmask_b32_e64 v154, v140, v144, s[10:11]
	v_cndmask_b32_e64 v155, v141, v145, s[10:11]
	v_cndmask_b32_e64 v156, v142, v146, s[10:11]
	v_cndmask_b32_e64 v157, v143, v147, s[10:11]
	v_pk_fma_f32 v[238:239], v[156:157], v[204:205], v[238:239]
	v_pk_fma_f32 v[236:237], v[154:155], v[202:203], v[236:237]
	global_store_dwordx4 v[216:217], v[236:239], off
	ds_bpermute_b32 v140, v211, v76
	ds_bpermute_b32 v144, v211, v72
	ds_bpermute_b32 v141, v211, v77
	ds_bpermute_b32 v145, v211, v73
	ds_bpermute_b32 v142, v211, v78
	ds_bpermute_b32 v146, v211, v74
	ds_bpermute_b32 v143, v211, v79
	ds_bpermute_b32 v147, v211, v75
	s_waitcnt lgkmcnt(0)
	v_cndmask_b32_e64 v154, v140, v144, s[10:11]
	v_cndmask_b32_e64 v155, v141, v145, s[10:11]
	v_cndmask_b32_e64 v156, v142, v146, s[10:11]
	v_cndmask_b32_e64 v157, v143, v147, s[10:11]
	v_pk_fma_f32 v[242:243], v[156:157], v[204:205], v[242:243]
	v_pk_fma_f32 v[240:241], v[154:155], v[202:203], v[240:241]
	global_store_dwordx4 v[218:219], v[240:243], off
	ds_bpermute_b32 v140, v210, v68
	ds_bpermute_b32 v144, v210, v64
	ds_bpermute_b32 v141, v210, v69
	ds_bpermute_b32 v145, v210, v65
	ds_bpermute_b32 v142, v210, v70
	ds_bpermute_b32 v146, v210, v66
	ds_bpermute_b32 v143, v210, v71
	ds_bpermute_b32 v147, v210, v67
	s_waitcnt lgkmcnt(0)
	v_cndmask_b32_e64 v154, v140, v144, s[10:11]
	v_cndmask_b32_e64 v155, v141, v145, s[10:11]
	v_cndmask_b32_e64 v156, v142, v146, s[10:11]
	v_cndmask_b32_e64 v157, v143, v147, s[10:11]
	v_pk_fma_f32 v[246:247], v[156:157], v[208:209], v[246:247]
	v_pk_fma_f32 v[244:245], v[154:155], v[206:207], v[244:245]
	global_store_dwordx4 v[216:217], v[244:247], off offset:512
	ds_bpermute_b32 v140, v211, v68
	ds_bpermute_b32 v144, v211, v64
	ds_bpermute_b32 v141, v211, v69
	ds_bpermute_b32 v145, v211, v65
	ds_bpermute_b32 v142, v211, v70
	ds_bpermute_b32 v146, v211, v66
	ds_bpermute_b32 v143, v211, v71
	ds_bpermute_b32 v147, v211, v67
	s_waitcnt lgkmcnt(0)
	v_cndmask_b32_e64 v154, v140, v144, s[10:11]
	v_cndmask_b32_e64 v155, v141, v145, s[10:11]
	v_cndmask_b32_e64 v156, v142, v146, s[10:11]
	v_cndmask_b32_e64 v157, v143, v147, s[10:11]
	v_pk_fma_f32 v[250:251], v[156:157], v[208:209], v[250:251]
	v_pk_fma_f32 v[248:249], v[154:155], v[206:207], v[248:249]
	global_store_dwordx4 v[218:219], v[248:251], off offset:512
	v_lshl_add_u64 v[212:213], v[212:213], 0, s[50:51]
	v_lshl_add_u64 v[214:215], v[214:215], 0, s[50:51]
	global_load_dwordx4 v[236:239], v[212:213], off
	global_load_dwordx4 v[240:243], v[214:215], off
	global_load_dwordx4 v[244:247], v[212:213], off offset:512
	global_load_dwordx4 v[248:251], v[214:215], off offset:512
	s_waitcnt vmcnt(8)
	v_lshl_add_u64 v[216:217], v[216:217], 0, s[8:9]
	v_lshl_add_u64 v[218:219], v[218:219], 0, s[8:9]
	ds_bpermute_b32 v140, v210, v60
	ds_bpermute_b32 v144, v210, v56
	ds_bpermute_b32 v141, v210, v61
	ds_bpermute_b32 v145, v210, v57
	ds_bpermute_b32 v142, v210, v62
	ds_bpermute_b32 v146, v210, v58
	ds_bpermute_b32 v143, v210, v63
	ds_bpermute_b32 v147, v210, v59
	s_waitcnt lgkmcnt(0)
	v_cndmask_b32_e64 v154, v140, v144, s[10:11]
	v_cndmask_b32_e64 v155, v141, v145, s[10:11]
	v_cndmask_b32_e64 v156, v142, v146, s[10:11]
	v_cndmask_b32_e64 v157, v143, v147, s[10:11]
	v_pk_fma_f32 v[222:223], v[156:157], v[204:205], v[222:223]
	v_pk_fma_f32 v[220:221], v[154:155], v[202:203], v[220:221]
	global_store_dwordx4 v[216:217], v[220:223], off
	ds_bpermute_b32 v140, v211, v60
	ds_bpermute_b32 v144, v211, v56
	ds_bpermute_b32 v141, v211, v61
	ds_bpermute_b32 v145, v211, v57
	ds_bpermute_b32 v142, v211, v62
	ds_bpermute_b32 v146, v211, v58
	ds_bpermute_b32 v143, v211, v63
	ds_bpermute_b32 v147, v211, v59
	s_waitcnt lgkmcnt(0)
	v_cndmask_b32_e64 v154, v140, v144, s[10:11]
	v_cndmask_b32_e64 v155, v141, v145, s[10:11]
	v_cndmask_b32_e64 v156, v142, v146, s[10:11]
	v_cndmask_b32_e64 v157, v143, v147, s[10:11]
	v_pk_fma_f32 v[226:227], v[156:157], v[204:205], v[226:227]
	v_pk_fma_f32 v[224:225], v[154:155], v[202:203], v[224:225]
	global_store_dwordx4 v[218:219], v[224:227], off
	ds_bpermute_b32 v140, v210, v52
	ds_bpermute_b32 v144, v210, v48
	ds_bpermute_b32 v141, v210, v53
	ds_bpermute_b32 v145, v210, v49
	ds_bpermute_b32 v142, v210, v54
	ds_bpermute_b32 v146, v210, v50
	ds_bpermute_b32 v143, v210, v55
	ds_bpermute_b32 v147, v210, v51
	s_waitcnt lgkmcnt(0)
	v_cndmask_b32_e64 v154, v140, v144, s[10:11]
	v_cndmask_b32_e64 v155, v141, v145, s[10:11]
	v_cndmask_b32_e64 v156, v142, v146, s[10:11]
	v_cndmask_b32_e64 v157, v143, v147, s[10:11]
	v_pk_fma_f32 v[230:231], v[156:157], v[208:209], v[230:231]
	v_pk_fma_f32 v[228:229], v[154:155], v[206:207], v[228:229]
	global_store_dwordx4 v[216:217], v[228:231], off offset:512
	ds_bpermute_b32 v140, v211, v52
	ds_bpermute_b32 v144, v211, v48
	ds_bpermute_b32 v141, v211, v53
	ds_bpermute_b32 v145, v211, v49
	ds_bpermute_b32 v142, v211, v54
	ds_bpermute_b32 v146, v211, v50
	ds_bpermute_b32 v143, v211, v55
	ds_bpermute_b32 v147, v211, v51
	s_waitcnt lgkmcnt(0)
;   DI void operator()(const pg8::f32x4 (&acc)[2][2][4][2], const pg8::Unit& u, int wr, int wc, int fr, int fq) const {
;     const int row0 = u.pm * 256 + wr * 64 + fr, col0 = u.pn * 256 + wc * 32 + 8 * fq;
;     const int b = (u.pm * 256) / TT;
; #pragma unroll
;     for (int ai = 0; ai < 2; ++ai)
; #pragma unroll
;       for (int m = 0; m < 4; ++m) {
;         const int row = row0 + ai * 128 + m * 16;
;         const int t = row - b * TT;
;         const bool isc = t >= TL;
;         float* dst = isc ? xc + ((size_t)b * TC + (t - TL)) * DM : xout + ((size_t)b * TL + t) * DM;
;         const float* src = src_input ? (isc ? cin + ((size_t)b * TC + (t - TL)) * DM : xin + ((size_t)b * TL + t) * DM) : dst;
;         const float* gate = modl + (size_t)(isc ? 16 : b) * 6144 + gi * DM;
; #pragma unroll
;         for (int bj = 0; bj < 2; ++bj) {
;           const int col = col0 + bj * 128;
; #pragma unroll
;           for (int n = 0; n < 2; ++n) {
;             pg8::f32x4 sv = *(const pg8::f32x4*)(src + col + 4 * n);
;             pg8::f32x4 gv = *(const pg8::f32x4*)(gate + col + 4 * n);
;             pg8::f32x4 o = sv + gv * acc[ai][bj][m][n];
;             *(pg8::f32x4*)(dst + col + 4 * n) = o;
;           }
;         }
;       }
;   }
	v_cndmask_b32_e64 v154, v140, v144, s[10:11]
	v_cndmask_b32_e64 v155, v141, v145, s[10:11]
	v_cndmask_b32_e64 v156, v142, v146, s[10:11]
	v_cndmask_b32_e64 v157, v143, v147, s[10:11]
	v_pk_fma_f32 v[234:235], v[156:157], v[208:209], v[234:235]
	v_pk_fma_f32 v[232:233], v[154:155], v[206:207], v[232:233]
	global_store_dwordx4 v[218:219], v[232:235], off offset:512
	v_lshl_add_u64 v[212:213], v[212:213], 0, s[50:51]
	v_lshl_add_u64 v[214:215], v[214:215], 0, s[50:51]
	global_load_dwordx4 v[220:223], v[212:213], off
	global_load_dwordx4 v[224:227], v[214:215], off
	global_load_dwordx4 v[228:231], v[212:213], off offset:512
	global_load_dwordx4 v[232:235], v[214:215], off offset:512
	s_waitcnt vmcnt(8)
	v_lshl_add_u64 v[216:217], v[216:217], 0, s[50:51]
	v_lshl_add_u64 v[218:219], v[218:219], 0, s[50:51]
	ds_bpermute_b32 v140, v210, v44
	ds_bpermute_b32 v144, v210, v40
	ds_bpermute_b32 v141, v210, v45
	ds_bpermute_b32 v145, v210, v41
	ds_bpermute_b32 v142, v210, v46
	ds_bpermute_b32 v146, v210, v42
	ds_bpermute_b32 v143, v210, v47
	ds_bpermute_b32 v147, v210, v43
	s_waitcnt lgkmcnt(0)
	v_cndmask_b32_e64 v154, v140, v144, s[10:11]
	v_cndmask_b32_e64 v155, v141, v145, s[10:11]
	v_cndmask_b32_e64 v156, v142, v146, s[10:11]
	v_cndmask_b32_e64 v157, v143, v147, s[10:11]
	v_pk_fma_f32 v[238:239], v[156:157], v[204:205], v[238:239]
	v_pk_fma_f32 v[236:237], v[154:155], v[202:203], v[236:237]
	global_store_dwordx4 v[216:217], v[236:239], off
	ds_bpermute_b32 v140, v211, v44
	ds_bpermute_b32 v144, v211, v40
	ds_bpermute_b32 v141, v211, v45
	ds_bpermute_b32 v145, v211, v41
	ds_bpermute_b32 v142, v211, v46
	ds_bpermute_b32 v146, v211, v42
	ds_bpermute_b32 v143, v211, v47
	ds_bpermute_b32 v147, v211, v43
	s_waitcnt lgkmcnt(0)
	v_cndmask_b32_e64 v154, v140, v144, s[10:11]
	v_cndmask_b32_e64 v155, v141, v145, s[10:11]
	v_cndmask_b32_e64 v156, v142, v146, s[10:11]
	v_cndmask_b32_e64 v157, v143, v147, s[10:11]
	v_pk_fma_f32 v[242:243], v[156:157], v[204:205], v[242:243]
	v_pk_fma_f32 v[240:241], v[154:155], v[202:203], v[240:241]
	global_store_dwordx4 v[218:219], v[240:243], off
	ds_bpermute_b32 v140, v210, v36
	ds_bpermute_b32 v144, v210, v32
	ds_bpermute_b32 v141, v210, v37
	ds_bpermute_b32 v145, v210, v33
	ds_bpermute_b32 v142, v210, v38
	ds_bpermute_b32 v146, v210, v34
	ds_bpermute_b32 v143, v210, v39
	ds_bpermute_b32 v147, v210, v35
	s_waitcnt lgkmcnt(0)
	v_cndmask_b32_e64 v154, v140, v144, s[10:11]
	v_cndmask_b32_e64 v155, v141, v145, s[10:11]
	v_cndmask_b32_e64 v156, v142, v146, s[10:11]
	v_cndmask_b32_e64 v157, v143, v147, s[10:11]
	v_pk_fma_f32 v[246:247], v[156:157], v[208:209], v[246:247]
	v_pk_fma_f32 v[244:245], v[154:155], v[206:207], v[244:245]
	global_store_dwordx4 v[216:217], v[244:247], off offset:512
	ds_bpermute_b32 v140, v211, v36
	ds_bpermute_b32 v144, v211, v32
	ds_bpermute_b32 v141, v211, v37
	ds_bpermute_b32 v145, v211, v33
	ds_bpermute_b32 v142, v211, v38
	ds_bpermute_b32 v146, v211, v34
	ds_bpermute_b32 v143, v211, v39
	ds_bpermute_b32 v147, v211, v35
	s_waitcnt lgkmcnt(0)
	v_cndmask_b32_e64 v154, v140, v144, s[10:11]
	v_cndmask_b32_e64 v155, v141, v145, s[10:11]
	v_cndmask_b32_e64 v156, v142, v146, s[10:11]
	v_cndmask_b32_e64 v157, v143, v147, s[10:11]
	v_pk_fma_f32 v[250:251], v[156:157], v[208:209], v[250:251]
	v_pk_fma_f32 v[248:249], v[154:155], v[206:207], v[248:249]
	global_store_dwordx4 v[218:219], v[248:251], off offset:512
	v_lshl_add_u64 v[212:213], v[212:213], 0, s[50:51]
	v_lshl_add_u64 v[214:215], v[214:215], 0, s[50:51]
	global_load_dwordx4 v[236:239], v[212:213], off
	global_load_dwordx4 v[240:243], v[214:215], off
	global_load_dwordx4 v[244:247], v[212:213], off offset:512
	global_load_dwordx4 v[248:251], v[214:215], off offset:512
	s_waitcnt vmcnt(8)
	v_lshl_add_u64 v[216:217], v[216:217], 0, s[50:51]
	v_lshl_add_u64 v[218:219], v[218:219], 0, s[50:51]
	ds_bpermute_b32 v140, v210, v28
	ds_bpermute_b32 v144, v210, v24
	ds_bpermute_b32 v141, v210, v29
	ds_bpermute_b32 v145, v210, v25
	ds_bpermute_b32 v142, v210, v30
	ds_bpermute_b32 v146, v210, v26
	ds_bpermute_b32 v143, v210, v31
	ds_bpermute_b32 v147, v210, v27
	s_waitcnt lgkmcnt(0)
	v_cndmask_b32_e64 v154, v140, v144, s[10:11]
	v_cndmask_b32_e64 v155, v141, v145, s[10:11]
	v_cndmask_b32_e64 v156, v142, v146, s[10:11]
	v_cndmask_b32_e64 v157, v143, v147, s[10:11]
	v_pk_fma_f32 v[222:223], v[156:157], v[204:205], v[222:223]
	v_pk_fma_f32 v[220:221], v[154:155], v[202:203], v[220:221]
	global_store_dwordx4 v[216:217], v[220:223], off
	ds_bpermute_b32 v140, v211, v28
	ds_bpermute_b32 v144, v211, v24
	ds_bpermute_b32 v141, v211, v29
	ds_bpermute_b32 v145, v211, v25
	ds_bpermute_b32 v142, v211, v30
	ds_bpermute_b32 v146, v211, v26
	ds_bpermute_b32 v143, v211, v31
	ds_bpermute_b32 v147, v211, v27
	s_waitcnt lgkmcnt(0)
; #define PG8_BAR __builtin_amdgcn_s_barrier()
; template <class Epi, class Sched, bool ALIGN_EPI = false, bool SP2 = false>
; __device__ __forceinline__ void gemm_phase(PG8_LAS unsigned char* lds, const Gemm g, const Sched& S, const Epi& E) {
;     ...
;         if constexpr (!Epi::AFTER_DRAIN) { E(acc, cur, wr, wc, fr, fq); S.done(cur); }
;         if (!has_next) break;
; #pragma unroll
;         for (int a = 0; a < 2; ++a)
; #pragma unroll
;             for (int b = 0; b < 2; ++b)
; #pragma unroll
;                 for (int m = 0; m < 4; ++m)
; #pragma unroll
;                     for (int n = 0; n < 2; ++n) acc[a][b][m][n] = (f32x4){0.f, 0.f, 0.f, 0.f};
;         cur = nxt; cA = nA; cB = nB; ++ui;
;         if constexpr (ALIGN_EPI) { if (wr == 1) PG8_BAR; }
;     }
;   DI void operator()(const pg8::f32x4 (&acc)[2][2][4][2], const pg8::Unit& u, int wr, int wc, int fr, int fq) const {
;     const int row0 = u.pm * 256 + wr * 64 + fr, col0 = u.pn * 256 + wc * 32 + 8 * fq;
;     const int b = (u.pm * 256) / TT;
; #pragma unroll
;     for (int ai = 0; ai < 2; ++ai)
; #pragma unroll
;       for (int m = 0; m < 4; ++m) {
;         const int row = row0 + ai * 128 + m * 16;
;         const int t = row - b * TT;
;         const bool isc = t >= TL;
;         float* dst = isc ? xc + ((size_t)b * TC + (t - TL)) * DM : xout + ((size_t)b * TL + t) * DM;
;         const float* src = src_input ? (isc ? cin + ((size_t)b * TC + (t - TL)) * DM : xin + ((size_t)b * TL + t) * DM) : dst;
;         const float* gate = modl + (size_t)(isc ? 16 : b) * 6144 + gi * DM;
; #pragma unroll
;         for (int bj = 0; bj < 2; ++bj) {
;           const int col = col0 + bj * 128;
; #pragma unroll
;           for (int n = 0; n < 2; ++n) {
;             pg8::f32x4 sv = *(const pg8::f32x4*)(src + col + 4 * n);
;             pg8::f32x4 gv = *(const pg8::f32x4*)(gate + col + 4 * n);
;             pg8::f32x4 o = sv + gv * acc[ai][bj][m][n];
;             *(pg8::f32x4*)(dst + col + 4 * n) = o;
;           }
;         }
;       }
;   }
	v_cndmask_b32_e64 v154, v140, v144, s[10:11]
	v_cndmask_b32_e64 v155, v141, v145, s[10:11]
	v_cndmask_b32_e64 v156, v142, v146, s[10:11]
	v_cndmask_b32_e64 v157, v143, v147, s[10:11]
	v_pk_fma_f32 v[226:227], v[156:157], v[204:205], v[226:227]
	v_pk_fma_f32 v[224:225], v[154:155], v[202:203], v[224:225]
	global_store_dwordx4 v[218:219], v[224:227], off
	ds_bpermute_b32 v140, v210, v20
	ds_bpermute_b32 v144, v210, v16
	ds_bpermute_b32 v141, v210, v21
	ds_bpermute_b32 v145, v210, v17
	ds_bpermute_b32 v142, v210, v22
	ds_bpermute_b32 v146, v210, v18
	ds_bpermute_b32 v143, v210, v23
	ds_bpermute_b32 v147, v210, v19
	s_waitcnt lgkmcnt(0)
	v_cndmask_b32_e64 v154, v140, v144, s[10:11]
	v_cndmask_b32_e64 v155, v141, v145, s[10:11]
	v_cndmask_b32_e64 v156, v142, v146, s[10:11]
	v_cndmask_b32_e64 v157, v143, v147, s[10:11]
	v_pk_fma_f32 v[230:231], v[156:157], v[208:209], v[230:231]
	v_pk_fma_f32 v[228:229], v[154:155], v[206:207], v[228:229]
	global_store_dwordx4 v[216:217], v[228:231], off offset:512
	ds_bpermute_b32 v140, v211, v20
	ds_bpermute_b32 v144, v211, v16
	ds_bpermute_b32 v141, v211, v21
	ds_bpermute_b32 v145, v211, v17
	ds_bpermute_b32 v142, v211, v22
	ds_bpermute_b32 v146, v211, v18
	ds_bpermute_b32 v143, v211, v23
	ds_bpermute_b32 v147, v211, v19
	s_waitcnt lgkmcnt(0)
	v_cndmask_b32_e64 v154, v140, v144, s[10:11]
	v_cndmask_b32_e64 v155, v141, v145, s[10:11]
	v_cndmask_b32_e64 v156, v142, v146, s[10:11]
	v_cndmask_b32_e64 v157, v143, v147, s[10:11]
	v_pk_fma_f32 v[234:235], v[156:157], v[208:209], v[234:235]
	v_pk_fma_f32 v[232:233], v[154:155], v[206:207], v[232:233]
	global_store_dwordx4 v[218:219], v[232:235], off offset:512
	s_waitcnt vmcnt(4)
	v_lshl_add_u64 v[216:217], v[216:217], 0, s[50:51]
	v_lshl_add_u64 v[218:219], v[218:219], 0, s[50:51]
	ds_bpermute_b32 v140, v210, v12
	ds_bpermute_b32 v144, v210, v8
	ds_bpermute_b32 v141, v210, v13
	ds_bpermute_b32 v145, v210, v9
	ds_bpermute_b32 v142, v210, v14
	ds_bpermute_b32 v146, v210, v10
	ds_bpermute_b32 v143, v210, v15
	ds_bpermute_b32 v147, v210, v11
	s_waitcnt lgkmcnt(0)
	v_cndmask_b32_e64 v154, v140, v144, s[10:11]
	v_cndmask_b32_e64 v155, v141, v145, s[10:11]
	v_cndmask_b32_e64 v156, v142, v146, s[10:11]
	v_cndmask_b32_e64 v157, v143, v147, s[10:11]
	v_pk_fma_f32 v[238:239], v[156:157], v[204:205], v[238:239]
	v_pk_fma_f32 v[236:237], v[154:155], v[202:203], v[236:237]
	global_store_dwordx4 v[216:217], v[236:239], off
	ds_bpermute_b32 v140, v211, v12
	ds_bpermute_b32 v144, v211, v8
	ds_bpermute_b32 v141, v211, v13
	ds_bpermute_b32 v145, v211, v9
	ds_bpermute_b32 v142, v211, v14
	ds_bpermute_b32 v146, v211, v10
	ds_bpermute_b32 v143, v211, v15
	ds_bpermute_b32 v147, v211, v11
	s_waitcnt lgkmcnt(0)
	v_cndmask_b32_e64 v154, v140, v144, s[10:11]
	v_cndmask_b32_e64 v155, v141, v145, s[10:11]
	v_cndmask_b32_e64 v156, v142, v146, s[10:11]
	v_cndmask_b32_e64 v157, v143, v147, s[10:11]
	v_pk_fma_f32 v[242:243], v[156:157], v[204:205], v[242:243]
	v_pk_fma_f32 v[240:241], v[154:155], v[202:203], v[240:241]
	global_store_dwordx4 v[218:219], v[240:243], off
	ds_bpermute_b32 v140, v210, v4
	ds_bpermute_b32 v144, v210, v0
	ds_bpermute_b32 v141, v210, v5
	ds_bpermute_b32 v145, v210, v1
	ds_bpermute_b32 v142, v210, v6
	ds_bpermute_b32 v146, v210, v2
	ds_bpermute_b32 v143, v210, v7
	ds_bpermute_b32 v147, v210, v3
	s_waitcnt lgkmcnt(0)
	v_cndmask_b32_e64 v154, v140, v144, s[10:11]
	v_cndmask_b32_e64 v155, v141, v145, s[10:11]
	v_cndmask_b32_e64 v156, v142, v146, s[10:11]
	v_cndmask_b32_e64 v157, v143, v147, s[10:11]
	v_pk_fma_f32 v[246:247], v[156:157], v[208:209], v[246:247]
	v_pk_fma_f32 v[244:245], v[154:155], v[206:207], v[244:245]
	global_store_dwordx4 v[216:217], v[244:247], off offset:512
	ds_bpermute_b32 v140, v211, v4
	ds_bpermute_b32 v144, v211, v0
	ds_bpermute_b32 v141, v211, v5
	ds_bpermute_b32 v145, v211, v1
	ds_bpermute_b32 v142, v211, v6
	ds_bpermute_b32 v146, v211, v2
	ds_bpermute_b32 v143, v211, v7
	ds_bpermute_b32 v147, v211, v3
	s_waitcnt lgkmcnt(0)
	v_cndmask_b32_e64 v154, v140, v144, s[10:11]
	v_cndmask_b32_e64 v155, v141, v145, s[10:11]
	v_cndmask_b32_e64 v156, v142, v146, s[10:11]
	v_cndmask_b32_e64 v157, v143, v147, s[10:11]
	v_pk_fma_f32 v[250:251], v[156:157], v[208:209], v[250:251]
	v_pk_fma_f32 v[248:249], v[154:155], v[206:207], v[248:249]
	global_store_dwordx4 v[218:219], v[248:251], off offset:512
	s_mov_b64 s[4:5], -1
	s_andn2_b64 vcc, exec, s[2:3]
	s_cbranch_vccnz .LBB0_1128
	s_andn2_b64 vcc, exec, s[16:17]
	s_cbranch_vccnz .LBB0_1127
	s_barrier
	s_branch .LBB0_1127
